# LDS staging writes interleaved into MFMA gaps: main GEMM k-loop (one ds_write per MFMA, lgkmcnt re-derived, single vmcnt wait) and T0 attention QK phase; plus T1 parked-Q prefetch
# speedup vs baseline: 1.0161x; 1.0161x over previous
; #define MFMA(a, b, c) __builtin_amdgcn_mfma_f32_32x32x16_bf16((a), (b), (c), 0, 0, 0)
; template <int DQK, int DV, int TYPE>
; DI void attn_item(int layer, int qt, int head, char* lds, const Params& P) {
;     ...
;     for (int j = 0; j < NT; ++j) {
;       const int tile = TILE_OF(j);
;       const char* sb = lds + (DB ? (j & 1) * STAGE : 0);
;       constexpr int KD = 2, KRING = 3;
;       bf16x8 kr0[KRING], kr1[KRING];
;     ...
; #pragma unroll
;       for (int s = 0; s < KD; ++s) KFR(s, s)
;       __builtin_amdgcn_sched_barrier(0);
;       if constexpr (DB) {
;         char* sn = lds + ((j + 1) & 1) * STAGE;
;         if (j + 1 < NT) { ATT_SSTORE(sn); }
;         if (j + 2 < NT) { ATT_GLOAD(TILE_OF(j + 2)); }
;       } else {
;         if (j + 1 < NT) { ATT_GLOAD(TILE_OF(j + 1)); }
;       }
;       f32x16 s0, s1;
; #pragma unroll
;       for (int i = 0; i < 16; ++i) { s0[i] = 0.f; s1[i] = 0.f; }
;       {
; #pragma unroll
;         for (int s = 0; s < NS; ++s) {
;           if (s + KD < NS) KFR(s + KD, (s + KD) % KRING)
;           bf16x8 qs;
;           if constexpr (NS > NQR) { if (s < NQR) qs = qf[s < NQR ? s : 0]; else qs = *reinterpret_cast<const bf16x8*>(qpark + (s - NQR) * 4096); }
;           else qs = qf[s];
;           s0 = MFMA(kr0[s % KRING], qs, s0);
;           s1 = MFMA(kr1[s % KRING], qs, s1);
;           __builtin_amdgcn_sched_barrier(0);
;         }
.LBB0_372:
	s_add_i32 s16, s5, -1
	s_bitcmp1_b32 s16, 0
	s_cselect_b32 s14, 0x6000, 0
	v_add_u32_e32 v0, s14, v168
	v_add_u32_e32 v15, v0, v164
	v_add_u32_e32 v14, v0, v165
	ds_read_b128 v[80:83], v15
	ds_read_b128 v[10:13], v15 offset:4096
	ds_read_b128 v[6:9], v14
	ds_read_b128 v[2:5], v14 offset:4096
	s_bitcmp1_b32 s5, 0
	s_cselect_b32 s14, 0x6000, 0
	s_add_i32 s14, s14, 0
	v_add_u32_e32 v194, s14, v162
	s_waitcnt vmcnt(0)
	s_waitcnt lgkmcnt(3)
	v_mfma_f32_32x32x16_bf16 v[96:111], v[80:83], v[124:127], 0
	ds_write_b128 v194, v[128:131]
	v_add_u32_e32 v172, v0, v166
	ds_read_b128 v[196:199], v172
	ds_read_b128 v[200:203], v172 offset:4096
	s_waitcnt lgkmcnt(5)
	v_mfma_f32_32x32x16_bf16 v[80:95], v[10:13], v[124:127], 0
	ds_write_b128 v194, v[132:135] offset:4096
	s_waitcnt lgkmcnt(5)
	v_mfma_f32_32x32x16_bf16 v[96:111], v[6:9], v[120:123], v[96:111]
	ds_write_b128 v194, v[136:139] offset:8192
	v_add_u32_e32 v173, v0, v167
	ds_read_b128 v[6:9], v173
	ds_read_b128 v[204:207], v173 offset:4096
	s_waitcnt lgkmcnt(7)
	v_mfma_f32_32x32x16_bf16 v[80:95], v[2:5], v[120:123], v[80:95]
	ds_write_b128 v194, v[140:143] offset:12288
	s_waitcnt lgkmcnt(6)
	v_mfma_f32_32x32x16_bf16 v[96:111], v[196:199], v[116:119], v[96:111]
	ds_write_b128 v194, v[144:147] offset:16384
	s_waitcnt lgkmcnt(6)
	v_mfma_f32_32x32x16_bf16 v[80:95], v[200:203], v[116:119], v[80:95]
	ds_write_b128 v194, v[148:151] offset:20480
	s_waitcnt lgkmcnt(4)
	v_mfma_f32_32x32x16_bf16 v[96:111], v[6:9], v[112:115], v[96:111]
	ds_read_b128 v[10:13], v15 offset:8192
	ds_read_b128 v[6:9], v14 offset:8192
	ds_read_b128 v[2:5], v172 offset:8192
	s_waitcnt lgkmcnt(6)
	v_mfma_f32_32x32x16_bf16 v[80:95], v[204:207], v[112:115], v[80:95]
	s_cmpk_gt_u32 s16, 0x101
	s_cbranch_scc1 .Lt0w_skip_a
	s_add_u32 s18, s12, s6
	s_addc_u32 s19, s13, s7
	s_add_u32 s16, s18, 0x9f82100
	s_addc_u32 s17, s19, 0
	v_lshl_add_u64 v[196:197], s[16:17], 0, v[154:155]
	s_add_u32 s16, s18, 0x9f92100
	s_addc_u32 s17, s19, 0
	s_add_u32 s18, s12, s0
	s_addc_u32 s19, s13, s1
	global_load_dwordx4 v[128:131], v[196:197], off
	v_lshl_add_u64 v[196:197], s[16:17], 0, v[154:155]
	s_add_u32 s16, s18, 0xbfc2200
	s_addc_u32 s17, s19, 0
	global_load_dwordx4 v[132:135], v[196:197], off
	v_lshl_add_u64 v[196:197], s[16:17], 0, v[152:153]
	s_add_u32 s16, s18, 0xc0c6200
	s_addc_u32 s17, s19, 0
	global_load_dwordx4 v[136:139], v[196:197], off
	v_lshl_add_u64 v[196:197], s[16:17], 0, v[152:153]
	s_add_u32 s16, s18, 0xc1ca200
	s_addc_u32 s17, s19, 0
	global_load_dwordx4 v[140:143], v[196:197], off
	v_lshl_add_u64 v[196:197], s[16:17], 0, v[152:153]
	s_add_u32 s16, s18, 0xc2ce200
	s_addc_u32 s17, s19, 0
	global_load_dwordx4 v[144:147], v[196:197], off
	v_lshl_add_u64 v[196:197], s[16:17], 0, v[152:153]
	global_load_dwordx4 v[148:151], v[196:197], off

; #define GL(...) GLOAD(__VA_ARGS__)
; template <bool TRANS>
; DI void gemm_kloop(const u16* __restrict__ A, int lda, const u16* __restrict__ W, int ldw, int K, f32x16 (&acc)[2][2], char* lds) {
;     ...
;   for (int kt = 0; kt < KT; kt += 2) {
;     const bool m2 = kt + 2 < KT;
;     if (m2) { GL(SET0, (kt + 2) * 64); }
.LBB0_465:
	s_cmp_lt_u32 s2, s14
	s_cselect_b64 s[68:69], -1, 0
	s_cmp_ge_u32 s2, s14
	s_cselect_b64 s[30:31], -1, 0
	s_and_b64 vcc, exec, s[30:31]
	v_lshl_add_u64 v[144:145], v[0:1], 0, s[28:29]
	v_lshl_add_u64 v[146:147], v[0:1], 0, s[22:23]
	v_lshl_add_u64 v[148:149], v[0:1], 0, s[50:51]
	v_lshl_add_u64 v[150:151], v[0:1], 0, s[98:99]
	v_lshl_add_u64 v[152:153], v[0:1], 0, s[24:25]
	v_lshl_add_u64 v[154:155], v[0:1], 0, s[6:7]
	v_lshl_add_u64 v[156:157], v[0:1], 0, s[46:47]
	v_lshl_add_u64 v[158:159], v[0:1], 0, s[16:17]
	s_cbranch_vccnz .Lwsa_last
	global_load_dwordx4 v[66:69], v[144:145], off offset:256
	global_load_dwordx4 v[70:73], v[146:147], off offset:256
	global_load_dwordx4 v[74:77], v[148:149], off offset:256
	global_load_dwordx4 v[78:81], v[150:151], off offset:256
	global_load_dwordx4 v[82:85], v[152:153], off offset:256
	global_load_dwordx4 v[86:89], v[154:155], off offset:256
	global_load_dwordx4 v[90:93], v[156:157], off offset:256
	global_load_dwordx4 v[94:97], v[158:159], off offset:256
	s_waitcnt vmcnt(8)
	s_branch .Lwsa_c0

; #define GL(...) GLOAD(__VA_ARGS__)
; #define SS(...) SSTORE(__VA_ARGS__)
; template <bool TRANS>
; DI void gemm_kloop(const u16* __restrict__ A, int lda, const u16* __restrict__ W, int ldw, int K, f32x16 (&acc)[2][2], char* lds) {
;     ...
;   for (int kt = 0; kt < KT; kt += 2) {
;     const bool m2 = kt + 2 < KT;
;     if (m2) { GL(SET0, (kt + 2) * 64); }
;     COMPUTE(0);
;     SS(SET1, 1);
;     __syncthreads();
;     if (m2) { GL(SET1, (kt + 3) * 64); }
;     COMPUTE(1);
;     if (m2) { SS(SET0, 0); }
;     __syncthreads();
;   }
.Lwsa_c0:
	v_add_u32_e32 v169, v165, v143
	ds_read_b128 v[196:199], v169 offset:16384
	v_add_u32_e32 v170, v164, v143
	ds_read_b128 v[200:203], v170
	ds_read_b128 v[204:207], v170 offset:4096
	ds_read_b128 v[208:211], v169 offset:20480
	v_add_u32_e32 v171, v164, v166
	v_add_u32_e32 v172, v165, v166
	s_waitcnt lgkmcnt(0)
	v_mfma_f32_32x32x16_bf16 v[50:65], v[208:211], v[200:203], v[50:65]
	ds_write_b128 v141, v[98:101] offset:32768
	v_mfma_f32_32x32x16_bf16 v[34:49], v[196:199], v[200:203], v[34:49]
	ds_write_b128 v141, v[102:105] offset:36864
	v_mfma_f32_32x32x16_bf16 v[2:17], v[196:199], v[204:207], v[2:17]
	ds_write_b128 v141, v[110:113] offset:40960
	ds_read_b128 v[196:199], v171
	ds_read_b128 v[200:203], v171 offset:4096
	ds_read_b128 v[212:215], v172 offset:16384
	ds_read_b128 v[226:229], v172 offset:20480
	v_mfma_f32_32x32x16_bf16 v[18:33], v[208:211], v[204:207], v[18:33]
	ds_write_b128 v141, v[106:109] offset:45056
	s_waitcnt lgkmcnt(2)
	v_mfma_f32_32x32x16_bf16 v[34:49], v[212:215], v[196:199], v[34:49]
	ds_write_b128 v141, v[114:117] offset:49152
	v_add_u32_e32 v173, v164, v167
	v_add_u32_e32 v190, v165, v167
	s_waitcnt lgkmcnt(2)
	v_mfma_f32_32x32x16_bf16 v[50:65], v[226:229], v[196:199], v[50:65]
	ds_write_b128 v141, v[122:125] offset:53248
	ds_read_b128 v[196:199], v173
	ds_read_b128 v[204:207], v173 offset:4096
	v_mfma_f32_32x32x16_bf16 v[2:17], v[212:215], v[200:203], v[2:17]
	ds_write_b128 v141, v[118:121] offset:57344
	ds_read_b128 v[208:211], v190 offset:16384
	ds_read_b128 v[212:215], v190 offset:20480
	v_mfma_f32_32x32x16_bf16 v[18:33], v[226:229], v[200:203], v[18:33]
	ds_write_b128 v141, v[126:129] offset:61440
	s_waitcnt lgkmcnt(2)
	v_mfma_f32_32x32x16_bf16 v[34:49], v[208:211], v[196:199], v[34:49]
	v_add_u32_e32 v194, v164, v168
	s_waitcnt lgkmcnt(1)
	v_mfma_f32_32x32x16_bf16 v[50:65], v[212:215], v[196:199], v[50:65]
	v_add_u32_e32 v196, v165, v168
	v_mfma_f32_32x32x16_bf16 v[2:17], v[208:211], v[204:207], v[2:17]
	ds_read_b128 v[198:201], v194
	ds_read_b128 v[208:211], v194 offset:4096
	ds_read_b128 v[226:229], v196 offset:16384
	ds_read_b128 v[230:233], v196 offset:20480
	v_mfma_f32_32x32x16_bf16 v[18:33], v[212:215], v[204:207], v[18:33]
	s_waitcnt lgkmcnt(1)
	v_mfma_f32_32x32x16_bf16 v[34:49], v[226:229], v[198:201], v[34:49]
	s_waitcnt lgkmcnt(0)
	v_mfma_f32_32x32x16_bf16 v[50:65], v[230:233], v[198:201], v[50:65]
	v_mfma_f32_32x32x16_bf16 v[2:17], v[226:229], v[208:211], v[2:17]
	v_mfma_f32_32x32x16_bf16 v[18:33], v[230:233], v[208:211], v[18:33]
	v_cndmask_b32_e64 v197, 0, 1, s[68:69]
	v_cmp_ne_u32_e64 s[42:43], 1, v197
	s_andn2_b64 vcc, exec, s[68:69]
	s_waitcnt lgkmcnt(0)
	s_barrier
	s_cbranch_vccnz .Lwsa_nol1
	global_load_dwordx4 v[98:101], v[144:145], off offset:384
	global_load_dwordx4 v[102:105], v[146:147], off offset:384
	global_load_dwordx4 v[110:113], v[148:149], off offset:384
	global_load_dwordx4 v[106:109], v[150:151], off offset:384
	global_load_dwordx4 v[114:117], v[152:153], off offset:384
	global_load_dwordx4 v[122:125], v[154:155], off offset:384
	global_load_dwordx4 v[118:121], v[156:157], off offset:384
	global_load_dwordx4 v[126:129], v[158:159], off offset:384
	s_waitcnt vmcnt(8)
	ds_read_b128 v[144:147], v169 offset:49152
	ds_read_b128 v[148:151], v170 offset:32768
	ds_read_b128 v[152:155], v170 offset:36864
	ds_read_b128 v[156:159], v169 offset:53248
	s_waitcnt lgkmcnt(2)
	v_mfma_f32_32x32x16_bf16 v[34:49], v[144:147], v[148:151], v[34:49]
	ds_write_b128 v141, v[66:69]
	s_waitcnt lgkmcnt(1)
	v_mfma_f32_32x32x16_bf16 v[50:65], v[156:159], v[148:151], v[50:65]
	ds_write_b128 v141, v[70:73] offset:4096
	v_mfma_f32_32x32x16_bf16 v[2:17], v[144:147], v[152:155], v[2:17]
	ds_write_b128 v141, v[74:77] offset:8192
	ds_read_b128 v[144:147], v171 offset:32768
	ds_read_b128 v[148:151], v171 offset:36864
	ds_read_b128 v[198:201], v172 offset:49152
	ds_read_b128 v[202:205], v172 offset:53248
	v_mfma_f32_32x32x16_bf16 v[18:33], v[156:159], v[152:155], v[18:33]
	ds_write_b128 v141, v[78:81] offset:12288
	s_waitcnt lgkmcnt(2)
	v_mfma_f32_32x32x16_bf16 v[34:49], v[198:201], v[144:147], v[34:49]
	ds_write_b128 v141, v[82:85] offset:16384
	s_waitcnt lgkmcnt(2)
	v_mfma_f32_32x32x16_bf16 v[50:65], v[202:205], v[144:147], v[50:65]
	ds_write_b128 v141, v[86:89] offset:20480
	ds_read_b128 v[144:147], v173 offset:32768
	ds_read_b128 v[152:155], v173 offset:36864
	ds_read_b128 v[156:159], v190 offset:49152
	ds_read_b128 v[170:173], v190 offset:53248
	v_mfma_f32_32x32x16_bf16 v[2:17], v[198:201], v[148:151], v[2:17]
	ds_write_b128 v141, v[90:93] offset:24576
	v_mfma_f32_32x32x16_bf16 v[18:33], v[202:205], v[148:151], v[18:33]
	ds_write_b128 v141, v[94:97] offset:28672
	s_waitcnt lgkmcnt(3)
	v_mfma_f32_32x32x16_bf16 v[34:49], v[156:159], v[144:147], v[34:49]
	s_waitcnt lgkmcnt(2)
	v_mfma_f32_32x32x16_bf16 v[50:65], v[170:173], v[144:147], v[50:65]
	v_mfma_f32_32x32x16_bf16 v[2:17], v[156:159], v[152:155], v[2:17]
	ds_read_b128 v[144:147], v194 offset:32768
	ds_read_b128 v[148:151], v194 offset:36864
	ds_read_b128 v[156:159], v196 offset:49152
	ds_read_b128 v[196:199], v196 offset:53248
	v_mfma_f32_32x32x16_bf16 v[18:33], v[170:173], v[152:155], v[18:33]
	s_waitcnt lgkmcnt(1)
	v_mfma_f32_32x32x16_bf16 v[34:49], v[156:159], v[144:147], v[34:49]
	s_waitcnt lgkmcnt(0)
	v_mfma_f32_32x32x16_bf16 v[50:65], v[196:199], v[144:147], v[50:65]
	v_mfma_f32_32x32x16_bf16 v[2:17], v[156:159], v[148:151], v[2:17]
	v_mfma_f32_32x32x16_bf16 v[18:33], v[196:199], v[148:151], v[18:33]
	s_branch .LBB0_464
; #define SS(...) SSTORE(__VA_ARGS__)
; template <bool TRANS>
; DI void gemm_kloop(const u16* __restrict__ A, int lda, const u16* __restrict__ W, int ldw, int K, f32x16 (&acc)[2][2], char* lds) {
;     ...
;     COMPUTE(1);
;     if (m2) { SS(SET0, 0); }
;     __syncthreads();
.Lwsa_nol1:
	ds_read_b128 v[144:147], v169 offset:49152
	ds_read_b128 v[148:151], v170 offset:32768
	ds_read_b128 v[152:155], v170 offset:36864
	ds_read_b128 v[156:159], v169 offset:53248
	s_waitcnt lgkmcnt(2)
	v_mfma_f32_32x32x16_bf16 v[34:49], v[144:147], v[148:151], v[34:49]
	s_waitcnt lgkmcnt(0)
	v_mfma_f32_32x32x16_bf16 v[50:65], v[156:159], v[148:151], v[50:65]
	v_mfma_f32_32x32x16_bf16 v[2:17], v[144:147], v[152:155], v[2:17]
	ds_read_b128 v[144:147], v171 offset:32768
	ds_read_b128 v[148:151], v171 offset:36864
	ds_read_b128 v[198:201], v172 offset:49152
	ds_read_b128 v[202:205], v172 offset:53248
	v_mfma_f32_32x32x16_bf16 v[18:33], v[156:159], v[152:155], v[18:33]
	s_waitcnt lgkmcnt(1)
	v_mfma_f32_32x32x16_bf16 v[34:49], v[198:201], v[144:147], v[34:49]
	s_waitcnt lgkmcnt(0)
	v_mfma_f32_32x32x16_bf16 v[50:65], v[202:205], v[144:147], v[50:65]
	ds_read_b128 v[144:147], v173 offset:32768
	ds_read_b128 v[152:155], v173 offset:36864
	ds_read_b128 v[156:159], v190 offset:49152
	ds_read_b128 v[170:173], v190 offset:53248
	v_mfma_f32_32x32x16_bf16 v[2:17], v[198:201], v[148:151], v[2:17]
	v_mfma_f32_32x32x16_bf16 v[18:33], v[202:205], v[148:151], v[18:33]
	s_waitcnt lgkmcnt(1)
	v_mfma_f32_32x32x16_bf16 v[34:49], v[156:159], v[144:147], v[34:49]
	s_waitcnt lgkmcnt(0)
	v_mfma_f32_32x32x16_bf16 v[50:65], v[170:173], v[144:147], v[50:65]
	v_mfma_f32_32x32x16_bf16 v[2:17], v[156:159], v[152:155], v[2:17]
	ds_read_b128 v[144:147], v194 offset:32768
	ds_read_b128 v[148:151], v194 offset:36864
	ds_read_b128 v[156:159], v196 offset:49152
	ds_read_b128 v[196:199], v196 offset:53248
	v_mfma_f32_32x32x16_bf16 v[18:33], v[170:173], v[152:155], v[18:33]
	s_waitcnt lgkmcnt(1)
	v_mfma_f32_32x32x16_bf16 v[34:49], v[156:159], v[144:147], v[34:49]
	s_waitcnt lgkmcnt(0)
	v_mfma_f32_32x32x16_bf16 v[50:65], v[196:199], v[144:147], v[50:65]
	v_mfma_f32_32x32x16_bf16 v[2:17], v[156:159], v[148:151], v[2:17]
	v_mfma_f32_32x32x16_bf16 v[18:33], v[196:199], v[148:151], v[18:33]
	s_branch .LBB0_464
